# mixprep schedule rebalanced: pool-mixer single-stage items moved from the tile-free workgroups to the ones that ran a second GEMM tile
# baseline (speedup 1.0000x reference)
.LBB0_260:
	s_add_i32 s29, s29, s42
	s_cmpk_gt_i32 s29, 0x4ff
	s_cbranch_scc1 .LBB0_323
.LBB0_261:
	s_and_b32 s4, s29, 0xff
	s_lshr_b32 s5, s29, 8
	s_and_b32 s6, s4, 31
	s_lshr_b32 s4, s4, 5
	s_cmp_ge_u32 s6, 19
	s_cbranch_scc0 .Lmp3_busy
	s_mul_i32 s4, s4, 13
	s_add_i32 s4, s4, s6
	s_sub_i32 s4, s4, 19
	s_mov_b32 s8, s4
	s_mov_b32 s10, 7
	s_cmp_eq_u32 s5, 0
	s_cbranch_scc1 .LBB0_265
	s_add_i32 s8, s4, 0x68
	s_mov_b32 s10, 4
	s_cmp_eq_u32 s5, 1
	s_cbranch_scc1 .LBB0_265
	s_cmp_eq_u32 s5, 2
	s_cbranch_scc0 .LBB0_260
	s_cmp_ge_u32 s4, 64
	s_cbranch_scc0 .LBB0_260
	s_mov_b32 s10, 2
	s_branch .LBB0_265

.Lmp3_b2r1:
	s_cmp_eq_u32 s5, 1
	s_cbranch_scc0 .LBB0_260
	s_add_i32 s8, s4, 0x68
	s_mov_b32 s10, 2
	s_branch .LBB0_265
.Lmp3_b3:
	s_sub_i32 s4, s4, 0x80
	s_mul_i32 s6, s5, 24
	s_add_i32 s8, s4, s6
	s_cmp_ge_u32 s8, 0x68
	s_cbranch_scc1 .LBB0_260
	s_add_i32 s8, s8, 0x68
	s_mov_b32 s10, 1
